# q12 + static s_setprio 1 for comp-1 waves inside the attention unit loop only
# speedup vs baseline: 1.0023x; 1.0012x over previous
.LBB0_1299:
	s_mov_b32 s2, s75
	v_readlane_b32 s0, v255, 8
	s_waitcnt vmcnt(12)
	v_mbcnt_lo_u32_b32 v3, -1, 0
	v_mbcnt_hi_u32_b32 v3, -1, v3
	s_mov_b64 s[4:5], s[58:59]
	s_load_dwordx2 s[14:15], s[4:5], 0xe0
	s_load_dwordx2 s[6:7], s[4:5], 0x98
	v_add_u32_e32 v107, s0, v3
	s_waitcnt vmcnt(11)
	v_bfe_i32 v6, v107, 27, 1
	v_lshlrev_b32_e32 v0, 4, v107
	v_lshrrev_b32_e32 v6, 22, v6
	v_add_u32_e32 v6, v0, v6
	v_and_b32_e32 v6, 0xfffffc00, v6
	v_sub_u32_e32 v6, v0, v6
	v_ashrrev_i32_e32 v2, 31, v107
	v_lshrrev_b32_e32 v7, 4, v6
	v_lshrrev_b32_e32 v2, 26, v2
	v_bitop3_b32 v6, v7, v6, 32 bitop3:0x6c
	s_waitcnt lgkmcnt(0)
	s_add_u32 s38, s14, 0x29c00000
	v_add_u32_e32 v2, v107, v2
	v_ashrrev_i32_e32 v8, 31, v6
	s_addc_u32 s39, s15, 0
	v_ashrrev_i32_e32 v2, 6, v2
	v_lshrrev_b32_e32 v8, 26, v8
	s_add_u32 s40, s14, 0x39a00000
	v_lshlrev_b32_e32 v7, 3, v2
	v_add_u32_e32 v8, v6, v8
	s_addc_u32 s41, s15, 0
	v_and_b32_e32 v7, -16, v7
	v_ashrrev_i32_e32 v9, 6, v8
	s_add_u32 s42, s14, 0x3aa00000
	v_add_u32_e32 v120, v9, v7
	v_and_b32_e32 v7, 0xc0, v8
	s_addc_u32 s43, s15, 0
	v_lshlrev_b32_e32 v2, 5, v2
	v_sub_u32_e32 v6, v6, v7
	v_mov_b32_e32 v9, 1
	s_add_u32 s52, s14, 0x3bc00000
	v_and_b32_e32 v2, 32, v2
	v_ashrrev_i16_sdwa v6, v9, sext(v6) dst_sel:DWORD dst_unused:UNUSED_PAD src0_sel:DWORD src1_sel:BYTE_0
	v_add_u32_e32 v0, 0x2000, v0
	s_addc_u32 s53, s15, 0
	v_add_u32_sdwa v121, v2, sext(v6) dst_sel:DWORD dst_unused:UNUSED_PAD src0_sel:DWORD src1_sel:WORD_0
	v_ashrrev_i32_e32 v2, 31, v0
	s_add_u32 s54, s14, 0x45800000
	v_lshrrev_b32_e32 v2, 22, v2
	s_addc_u32 s55, s15, 0
	s_lshl_b32 s4, s60, 7
	s_mov_b32 s5, s75
	v_add_u32_e32 v2, v0, v2
	s_lshl_b64 s[4:5], s[4:5], 2
	v_ashrrev_i32_e32 v2, 10, v2
	s_add_u32 s10, s6, s4
	v_mul_i32_i24_e32 v6, 0x400, v2
	s_addc_u32 s11, s7, s5
	s_lshl_b32 s6, s60, 6
	s_mov_b32 s7, s75
	v_sub_u32_e32 v0, v0, v6
	s_lshl_b64 s[6:7], s[6:7], 2
	v_lshrrev_b32_e32 v6, 4, v0
	s_add_u32 s0, s14, s6
	v_bitop3_b32 v0, v6, v0, 32 bitop3:0x6c
	s_addc_u32 s6, s15, s7
	v_ashrrev_i32_e32 v7, 31, v0
	s_add_u32 s16, s0, 0x10000
	v_lshrrev_b32_e32 v7, 26, v7
	s_addc_u32 s17, s6, 0
	s_add_i32 s56, s2, 0x23f40
	v_lshlrev_b32_e32 v6, 3, v2
	v_add_u32_e32 v7, v0, v7
	s_add_u32 s57, s14, 0x21800000
	v_and_b32_e32 v6, 0x7ffffff0, v6
	v_ashrrev_i32_e32 v8, 6, v7
	s_addc_u32 s58, s15, 0
	s_lshl_b64 s[12:13], s[74:75], 2
	v_add_u32_e32 v122, v8, v6
	v_and_b32_e32 v6, 0xc0, v7
	s_add_u32 s0, s14, s12
	v_lshlrev_b32_e32 v2, 5, v2
	v_sub_u32_e32 v0, v0, v6
	s_addc_u32 s8, s15, s13
	v_and_b32_e32 v2, 32, v2
	v_ashrrev_i16_sdwa v0, v9, sext(v0) dst_sel:DWORD dst_unused:UNUSED_PAD src0_sel:DWORD src1_sel:BYTE_0
	s_add_u32 s18, s0, 0x200000
	v_and_b32_e32 v4, 63, v3
	v_and_b32_e32 v109, 15, v3
	v_bfe_u32 v5, v3, 4, 2
	v_add_u32_sdwa v123, v2, sext(v0) dst_sel:DWORD dst_unused:UNUSED_PAD src0_sel:DWORD src1_sel:WORD_0
	v_and_b32_e32 v0, 48, v3
	v_lshlrev_b32_e32 v3, 2, v3
	s_addc_u32 s19, s8, 0
	v_and_b32_e32 v3, 32, v3
	v_lshlrev_b32_e32 v6, 6, v109
	v_cmp_gt_u32_e64 s[8:9], 16, v4
	v_lshlrev_b32_e32 v4, 2, v4
	v_lshlrev_b32_e32 v2, 3, v5
	v_or_b32_e32 v7, v6, v0
	v_bitop3_b32 v6, v6, v3, v0 bitop3:0x36
	v_xor_b32_e32 v125, 64, v4
	v_xor_b32_e32 v126, 0x80, v4
	v_lshlrev_b32_e32 v4, 11, v109
	v_readlane_b32 s20, v254, 19
	v_cmp_eq_u32_e64 s[6:7], 0, v107
	s_add_i32 s59, s2, 0x10000
	s_add_i32 s60, s2, 0x14000
	v_add_u32_e32 v124, s2, v6
	v_lshlrev_b32_e32 v106, 2, v5
	v_add_u32_e32 v108, s2, v0
	v_lshl_add_u64 v[110:111], s[10:11], 0, v[0:1]
	v_bitop3_b32 v127, v7, s1, v3 bitop3:0xde
	v_lshlrev_b32_e32 v128, 1, v4
	v_lshlrev_b32_e32 v112, 1, v2
	v_readlane_b32 s21, v254, 20
	v_readfirstlane_b32 s0, v107
	s_nop 3
	s_cmpk_lt_u32 s0, 0x100
	s_cbranch_scc1 .Latt_prio_skip
	s_setprio 1
.Latt_prio_skip:
	s_branch .LBB0_1301

.LBB0_1342:
	s_setprio 0
	v_readlane_b32 s58, v254, 3
	v_readlane_b32 s59, v254, 4
	s_mov_b32 s49, s75
	s_mov_b64 s[8:9], s[58:59]
	s_getreg_b32 s0, hwreg(HW_REG_XCC_ID, 0, 4)
	v_mbcnt_lo_u32_b32 v0, -1, 0
	v_mbcnt_hi_u32_b32 v0, -1, v0
	s_waitcnt vmcnt(0)
	v_readlane_b32 s2, v254, 5
	s_waitcnt vmcnt(0)
	s_barrier
	v_cmp_eq_u32_e32 vcc, s2, v0
	s_and_saveexec_b64 s[6:7], vcc
	s_cbranch_execz .LBB0_1395
	s_add_i32 s2, s49, 0x23f20
	v_mov_b32_e32 v0, s2
	s_load_dwordx2 s[8:9], s[8:9], 0xe0
	s_waitcnt vmcnt(0) expcnt(0) lgkmcnt(0)
	ds_read_b32 v3, v0
	s_add_i32 s49, s49, 0x23f24
	v_mov_b32_e32 v0, s49
	ds_read_b32 v2, v0
	s_and_b32 s0, s0, 15
	s_waitcnt lgkmcnt(1)
	v_cmp_ne_u32_e32 vcc, 0, v3
	s_cbranch_vccnz .LBB0_1359
	v_readlane_b32 s10, v254, 0
	v_readlane_b32 s11, v254, 1
	s_load_dwordx2 s[16:17], s[10:11], 0x4
	s_add_u32 s10, s8, 0x4200
	s_addc_u32 s11, s9, 0
	s_add_u32 s14, s8, 0x4400
	s_addc_u32 s15, s9, 0
	s_waitcnt lgkmcnt(0)
	s_mul_i32 s60, s16, s3
	s_add_u32 s16, s8, 0x4500
	s_mul_i32 s60, s60, s17
	s_addc_u32 s17, s9, 0
	s_add_u32 s18, s8, 0x4600
	s_addc_u32 s19, s9, 0
	s_add_u32 s20, s8, 0x4700
	s_addc_u32 s21, s9, 0
	s_add_u32 s22, s8, 0x4800
	s_addc_u32 s23, s9, 0
	s_add_u32 s24, s8, 0x4900
	s_addc_u32 s25, s9, 0
	s_add_u32 s26, s8, 0x4a00
	s_addc_u32 s27, s9, 0
	s_add_u32 s28, s8, 0x4b00
	s_addc_u32 s29, s9, 0
	s_add_u32 s30, s8, 0x4c00
	s_addc_u32 s31, s9, 0
	s_add_u32 s34, s8, 0x4d00
	s_addc_u32 s35, s9, 0
	s_add_u32 s36, s8, 0x4e00
	s_addc_u32 s37, s9, 0
	s_add_u32 s38, s8, 0x4f00
	s_addc_u32 s39, s9, 0
	s_add_u32 s40, s8, 0x5000
	s_addc_u32 s41, s9, 0
	s_add_u32 s42, s8, 0x5100
	s_addc_u32 s43, s9, 0
	s_add_u32 s50, s8, 0x5200
	s_addc_u32 s51, s9, 0
	s_add_u32 s52, s8, 0x5300
	s_addc_u32 s53, s9, 0
	s_mov_b32 s61, 1
	s_branch .LBB0_1347
